# residual epilogues of w_o and MLP-out: old-residual f32 loads and new-residual f32 stores marked streaming (nt)
# baseline (speedup 1.0000x reference)
.LBB0_1230:
	v_lshl_add_u32 v200, s58, 8, v231
	v_lshl_or_b32 v196, s56, 8, v233
	v_ashrrev_i32_e32 v197, 31, v196
	v_ashrrev_i32_e32 v201, 31, v200
	v_lshl_add_u64 v[198:199], v[196:197], 2, s[2:3]
	v_lshlrev_b64 v[126:127], 13, v[200:201]
	v_lshl_add_u64 v[126:127], v[198:199], 0, v[126:127]
	global_load_dwordx4 v[186:189], v[126:127], off nt
	global_load_dwordx4 v[218:221], v[126:127], off offset:64 nt
	global_load_dwordx4 v[182:185], v[126:127], off offset:512 nt
	global_load_dwordx4 v[178:181], v[126:127], off offset:576 nt
	v_or_b32_e32 v206, 16, v200
	v_ashrrev_i32_e32 v207, 31, v206
	v_lshlrev_b64 v[126:127], 13, v[206:207]
	v_or_b32_e32 v204, 32, v200
	v_lshl_add_u64 v[126:127], v[198:199], 0, v[126:127]
	v_ashrrev_i32_e32 v205, 31, v204
	global_load_dwordx4 v[174:177], v[126:127], off nt
	global_load_dwordx4 v[170:173], v[126:127], off offset:64 nt
	global_load_dwordx4 v[166:169], v[126:127], off offset:512 nt
	global_load_dwordx4 v[162:165], v[126:127], off offset:576 nt
	v_lshlrev_b64 v[126:127], 13, v[204:205]
	v_or_b32_e32 v202, 48, v200
	v_lshl_add_u64 v[126:127], v[198:199], 0, v[126:127]
	v_ashrrev_i32_e32 v203, 31, v202
	global_load_dwordx4 v[158:161], v[126:127], off nt
	global_load_dwordx4 v[154:157], v[126:127], off offset:64 nt
	global_load_dwordx4 v[146:149], v[126:127], off offset:512 nt
	global_load_dwordx4 v[134:137], v[126:127], off offset:576 nt
	v_lshlrev_b64 v[126:127], 13, v[202:203]
	v_lshl_add_u64 v[126:127], v[198:199], 0, v[126:127]
	global_load_dwordx4 v[150:153], v[126:127], off nt
	global_load_dwordx4 v[138:141], v[126:127], off offset:64 nt
	global_load_dwordx4 v[130:133], v[126:127], off offset:512 nt
	s_nop 0
	global_load_dwordx4 v[126:129], v[126:127], off offset:576 nt
	v_lshlrev_b64 v[208:209], 11, v[200:201]
	v_lshl_add_u64 v[208:209], v[208:209], 0, v[196:197]
	s_lshl_b32 s56, s56, 2
	s_ashr_i32 s57, s56, 31
	s_waitcnt vmcnt(0)
	v_pk_add_f32 v[144:145], v[144:145], v[188:189]
	v_pk_add_f32 v[142:143], v[142:143], v[186:187]
	v_lshl_add_u64 v[186:187], v[208:209], 2, s[30:31]
	global_store_dwordx4 v[186:187], v[142:145], off nt
	v_mul_f32_e32 v186, v143, v143
	v_mul_f32_e32 v187, v145, v145
	v_fmac_f32_e32 v186, v142, v142
	v_fmac_f32_e32 v187, v144, v144
	v_cvt_pk_bf16_f32 v142, v142, v143
	v_cvt_pk_bf16_f32 v143, v144, v145
	v_lshl_add_u64 v[144:145], v[208:209], 1, s[36:37]
	global_store_dwordx2 v[144:145], v[142:143], off
	v_or_b32_e32 v142, 16, v208
	v_mov_b32_e32 v143, v209
	v_pk_add_f32 v[124:125], v[124:125], v[220:221]
	v_pk_add_f32 v[122:123], v[122:123], v[218:219]
	v_lshl_add_u64 v[144:145], v[142:143], 2, s[30:31]
	global_store_dwordx4 v[144:145], v[122:125], off nt
	v_mul_f32_e32 v144, v123, v123
	v_mul_f32_e32 v145, v125, v125
	v_fmac_f32_e32 v144, v122, v122
	v_fmac_f32_e32 v145, v124, v124
	v_cvt_pk_bf16_f32 v122, v122, v123
	v_cvt_pk_bf16_f32 v123, v124, v125
	v_lshl_add_u64 v[124:125], v[142:143], 1, s[36:37]
	global_store_dwordx2 v[124:125], v[122:123], off
	v_or_b32_e32 v122, 0x80, v208
	v_mov_b32_e32 v123, v209
	v_pk_add_f32 v[120:121], v[120:121], v[184:185]
	v_pk_add_f32 v[118:119], v[118:119], v[182:183]
	v_lshl_add_u64 v[124:125], v[122:123], 2, s[30:31]
	global_store_dwordx4 v[124:125], v[118:121], off nt
	v_mul_f32_e32 v124, v119, v119
	v_mul_f32_e32 v125, v121, v121
	v_fmac_f32_e32 v124, v118, v118
	v_fmac_f32_e32 v125, v120, v120
	v_cvt_pk_bf16_f32 v118, v118, v119
	v_cvt_pk_bf16_f32 v119, v120, v121
	v_lshl_add_u64 v[120:121], v[122:123], 1, s[36:37]
	v_or_b32_e32 v208, 0x90, v208
	global_store_dwordx2 v[120:121], v[118:119], off
	v_pk_add_f32 v[116:117], v[116:117], v[180:181]
	v_pk_add_f32 v[114:115], v[114:115], v[178:179]
	v_lshl_add_u64 v[118:119], v[208:209], 2, s[30:31]
	global_store_dwordx4 v[118:119], v[114:117], off nt
	v_mul_f32_e32 v118, v115, v115
	v_mul_f32_e32 v119, v117, v117
	v_fmac_f32_e32 v118, v114, v114
	v_fmac_f32_e32 v119, v116, v116
	v_cvt_pk_bf16_f32 v114, v114, v115
	v_cvt_pk_bf16_f32 v115, v116, v117
	v_lshl_add_u64 v[116:117], v[208:209], 1, s[36:37]
	v_add_f32_e32 v186, v186, v187
	v_add_f32_e32 v144, v144, v145
	global_store_dwordx2 v[116:117], v[114:115], off
	v_xor_b32_e32 v114, 16, v213
	v_add_f32_e32 v144, v186, v144
	v_add_f32_e32 v124, v124, v125
	v_cmp_lt_i32_e32 vcc, v114, v216
	v_add_f32_e32 v124, v144, v124
	v_add_f32_e32 v118, v118, v119
	v_cndmask_b32_e32 v114, v213, v114, vcc
	v_add_f32_e32 v118, v124, v118
	v_lshlrev_b32_e32 v142, 2, v114
	ds_bpermute_b32 v114, v142, v118
	v_xor_b32_e32 v115, 32, v213
	v_cmp_lt_i32_e32 vcc, v115, v216
	s_waitcnt lgkmcnt(0)
	v_add_f32_e32 v114, v118, v114
	v_cndmask_b32_e32 v115, v213, v115, vcc
	v_lshlrev_b32_e32 v143, 2, v115
	ds_bpermute_b32 v115, v143, v114
	s_and_saveexec_b64 s[4:5], s[40:41]
	s_cbranch_execz .LBB0_1232
	v_lshlrev_b64 v[116:117], 7, v[200:201]
	v_lshl_add_u64 v[116:117], s[44:45], 0, v[116:117]
	v_lshl_add_u64 v[116:117], s[56:57], 2, v[116:117]
	s_lshl_b32 s10, s23, 2
	v_lshl_add_u64 v[116:117], v[116:117], 0, s[10:11]
	s_waitcnt lgkmcnt(0)
	v_add_f32_e32 v114, v114, v115
	global_store_dword v[116:117], v114, off
.LBB0_1232:
	s_or_b64 exec, exec, s[4:5]
	s_waitcnt lgkmcnt(0)
	v_lshlrev_b64 v[114:115], 11, v[206:207]
	v_lshl_add_u64 v[114:115], v[114:115], 0, v[196:197]
	v_pk_add_f32 v[112:113], v[112:113], v[176:177]
	v_pk_add_f32 v[110:111], v[110:111], v[174:175]
	v_lshl_add_u64 v[116:117], v[114:115], 2, s[30:31]
	global_store_dwordx4 v[116:117], v[110:113], off nt
	v_mul_f32_e32 v116, v111, v111
	v_mul_f32_e32 v117, v113, v113
	v_fmac_f32_e32 v116, v110, v110
	v_fmac_f32_e32 v117, v112, v112
	v_cvt_pk_bf16_f32 v110, v110, v111
	v_cvt_pk_bf16_f32 v111, v112, v113
	v_lshl_add_u64 v[112:113], v[114:115], 1, s[36:37]
	global_store_dwordx2 v[112:113], v[110:111], off
	v_or_b32_e32 v110, 16, v114
	v_mov_b32_e32 v111, v115
	v_pk_add_f32 v[108:109], v[108:109], v[172:173]
	v_pk_add_f32 v[106:107], v[106:107], v[170:171]
	v_lshl_add_u64 v[112:113], v[110:111], 2, s[30:31]
	global_store_dwordx4 v[112:113], v[106:109], off nt
	v_mul_f32_e32 v112, v107, v107
	v_mul_f32_e32 v113, v109, v109
	v_fmac_f32_e32 v112, v106, v106
	v_fmac_f32_e32 v113, v108, v108
	v_cvt_pk_bf16_f32 v106, v106, v107
	v_cvt_pk_bf16_f32 v107, v108, v109
	v_lshl_add_u64 v[108:109], v[110:111], 1, s[36:37]
	global_store_dwordx2 v[108:109], v[106:107], off
	v_or_b32_e32 v106, 0x80, v114
	v_mov_b32_e32 v107, v115
	v_pk_add_f32 v[104:105], v[104:105], v[168:169]
	v_pk_add_f32 v[102:103], v[102:103], v[166:167]
	v_lshl_add_u64 v[108:109], v[106:107], 2, s[30:31]
	global_store_dwordx4 v[108:109], v[102:105], off nt
	v_mul_f32_e32 v108, v103, v103
	v_mul_f32_e32 v109, v105, v105
	v_add_f32_e32 v116, v116, v117
	v_add_f32_e32 v112, v112, v113
	v_fmac_f32_e32 v108, v102, v102
	v_fmac_f32_e32 v109, v104, v104
	v_add_f32_e32 v112, v116, v112
	v_add_f32_e32 v108, v108, v109
	v_add_f32_e32 v110, v112, v108
	v_cvt_pk_bf16_f32 v108, v102, v103
	v_pk_add_f32 v[102:103], v[100:101], v[164:165]
	v_pk_add_f32 v[100:101], v[98:99], v[162:163]
	v_mul_f32_e32 v99, v103, v103
	v_mul_f32_e32 v98, v101, v101
	v_fmac_f32_e32 v98, v100, v100
	v_fmac_f32_e32 v99, v102, v102
	v_add_f32_e32 v98, v98, v99
	v_cvt_pk_bf16_f32 v109, v104, v105
	v_lshl_add_u64 v[104:105], v[106:107], 1, s[36:37]
	v_add_f32_e32 v106, v110, v98
	ds_bpermute_b32 v107, v142, v106
	v_or_b32_e32 v114, 0x90, v114
	v_lshl_add_u64 v[98:99], v[114:115], 2, s[30:31]
	global_store_dwordx2 v[104:105], v[108:109], off
	global_store_dwordx4 v[98:99], v[100:103], off nt
	s_waitcnt lgkmcnt(0)
	v_add_f32_e32 v98, v106, v107
	ds_bpermute_b32 v99, v143, v98
	v_cvt_pk_bf16_f32 v100, v100, v101
	v_cvt_pk_bf16_f32 v101, v102, v103
	v_lshl_add_u64 v[102:103], v[114:115], 1, s[36:37]
	global_store_dwordx2 v[102:103], v[100:101], off
	s_and_saveexec_b64 s[4:5], s[40:41]
	s_cbranch_execz .LBB0_1234
	v_lshlrev_b64 v[100:101], 7, v[206:207]
	v_lshl_add_u64 v[100:101], s[44:45], 0, v[100:101]
	v_lshl_add_u64 v[100:101], s[56:57], 2, v[100:101]
	s_lshl_b32 s10, s23, 2
	v_lshl_add_u64 v[100:101], v[100:101], 0, s[10:11]
	s_waitcnt lgkmcnt(0)
	v_add_f32_e32 v98, v98, v99
	global_store_dword v[100:101], v98, off
.LBB0_1234:
	s_or_b64 exec, exec, s[4:5]
	s_waitcnt lgkmcnt(0)
	v_lshlrev_b64 v[98:99], 11, v[204:205]
	v_lshl_add_u64 v[98:99], v[98:99], 0, v[196:197]
	v_pk_add_f32 v[96:97], v[96:97], v[160:161]
	v_pk_add_f32 v[94:95], v[94:95], v[158:159]
	v_lshl_add_u64 v[100:101], v[98:99], 2, s[30:31]
	global_store_dwordx4 v[100:101], v[94:97], off nt
	v_mul_f32_e32 v100, v95, v95
	v_mul_f32_e32 v101, v97, v97
	v_fmac_f32_e32 v100, v94, v94
	v_fmac_f32_e32 v101, v96, v96
	v_cvt_pk_bf16_f32 v94, v94, v95
	v_cvt_pk_bf16_f32 v95, v96, v97
	v_lshl_add_u64 v[96:97], v[98:99], 1, s[36:37]
	global_store_dwordx2 v[96:97], v[94:95], off
	v_or_b32_e32 v94, 16, v98
	v_mov_b32_e32 v95, v99
	v_pk_add_f32 v[92:93], v[92:93], v[156:157]
	v_pk_add_f32 v[90:91], v[90:91], v[154:155]
	v_lshl_add_u64 v[96:97], v[94:95], 2, s[30:31]
	global_store_dwordx4 v[96:97], v[90:93], off nt
	v_mul_f32_e32 v96, v91, v91
	v_mul_f32_e32 v97, v93, v93
	v_fmac_f32_e32 v96, v90, v90
	v_fmac_f32_e32 v97, v92, v92
	v_cvt_pk_bf16_f32 v90, v90, v91
	v_cvt_pk_bf16_f32 v91, v92, v93
	v_lshl_add_u64 v[92:93], v[94:95], 1, s[36:37]
	global_store_dwordx2 v[92:93], v[90:91], off
	v_or_b32_e32 v90, 0x80, v98
	v_mov_b32_e32 v91, v99
	v_pk_add_f32 v[88:89], v[88:89], v[148:149]
	v_pk_add_f32 v[86:87], v[86:87], v[146:147]
	v_lshl_add_u64 v[92:93], v[90:91], 2, s[30:31]
	global_store_dwordx4 v[92:93], v[86:89], off nt
	v_mul_f32_e32 v92, v87, v87
	v_mul_f32_e32 v93, v89, v89
	v_add_f32_e32 v100, v100, v101
	v_add_f32_e32 v96, v96, v97
	v_fmac_f32_e32 v92, v86, v86
	v_fmac_f32_e32 v93, v88, v88
	v_add_f32_e32 v96, v100, v96
	v_add_f32_e32 v92, v92, v93
	v_add_f32_e32 v94, v96, v92
	v_cvt_pk_bf16_f32 v92, v86, v87
	v_pk_add_f32 v[86:87], v[84:85], v[136:137]
	v_pk_add_f32 v[84:85], v[82:83], v[134:135]
	v_mul_f32_e32 v83, v87, v87
	v_mul_f32_e32 v82, v85, v85
	v_fmac_f32_e32 v82, v84, v84
	v_fmac_f32_e32 v83, v86, v86
	v_add_f32_e32 v82, v82, v83
	v_cvt_pk_bf16_f32 v93, v88, v89
	v_lshl_add_u64 v[88:89], v[90:91], 1, s[36:37]
	v_add_f32_e32 v90, v94, v82
	ds_bpermute_b32 v91, v142, v90
	v_or_b32_e32 v98, 0x90, v98
	v_lshl_add_u64 v[82:83], v[98:99], 2, s[30:31]
	global_store_dwordx2 v[88:89], v[92:93], off
	global_store_dwordx4 v[82:83], v[84:87], off nt
	s_waitcnt lgkmcnt(0)
	v_add_f32_e32 v82, v90, v91
	ds_bpermute_b32 v83, v143, v82
	v_cvt_pk_bf16_f32 v84, v84, v85
	v_cvt_pk_bf16_f32 v85, v86, v87
	v_lshl_add_u64 v[86:87], v[98:99], 1, s[36:37]
	global_store_dwordx2 v[86:87], v[84:85], off
	s_and_saveexec_b64 s[4:5], s[40:41]
	s_cbranch_execz .LBB0_1236
	v_lshlrev_b64 v[84:85], 7, v[204:205]
	v_lshl_add_u64 v[84:85], s[44:45], 0, v[84:85]
	v_lshl_add_u64 v[84:85], s[56:57], 2, v[84:85]
	s_lshl_b32 s10, s23, 2
	v_lshl_add_u64 v[84:85], v[84:85], 0, s[10:11]
	s_waitcnt lgkmcnt(0)
	v_add_f32_e32 v82, v82, v83
	global_store_dword v[84:85], v82, off
.LBB0_1236:
	s_or_b64 exec, exec, s[4:5]
	s_waitcnt lgkmcnt(0)
	v_lshlrev_b64 v[82:83], 11, v[202:203]
	v_lshl_add_u64 v[82:83], v[82:83], 0, v[196:197]
	v_pk_add_f32 v[80:81], v[80:81], v[152:153]
	v_pk_add_f32 v[78:79], v[78:79], v[150:151]
	v_lshl_add_u64 v[84:85], v[82:83], 2, s[30:31]
	global_store_dwordx4 v[84:85], v[78:81], off nt
	v_mul_f32_e32 v84, v79, v79
	v_mul_f32_e32 v85, v81, v81
	v_fmac_f32_e32 v84, v78, v78
	v_fmac_f32_e32 v85, v80, v80
	v_cvt_pk_bf16_f32 v78, v78, v79
	v_cvt_pk_bf16_f32 v79, v80, v81
	v_lshl_add_u64 v[80:81], v[82:83], 1, s[36:37]
	global_store_dwordx2 v[80:81], v[78:79], off
	v_or_b32_e32 v78, 16, v82
	v_mov_b32_e32 v79, v83
	v_pk_add_f32 v[76:77], v[76:77], v[140:141]
	v_pk_add_f32 v[74:75], v[74:75], v[138:139]
	v_lshl_add_u64 v[80:81], v[78:79], 2, s[30:31]
	global_store_dwordx4 v[80:81], v[74:77], off nt
	v_mul_f32_e32 v80, v75, v75
	v_mul_f32_e32 v81, v77, v77
	v_fmac_f32_e32 v80, v74, v74
	v_fmac_f32_e32 v81, v76, v76
	v_cvt_pk_bf16_f32 v74, v74, v75
	v_cvt_pk_bf16_f32 v75, v76, v77
	v_lshl_add_u64 v[76:77], v[78:79], 1, s[36:37]
	global_store_dwordx2 v[76:77], v[74:75], off
	v_or_b32_e32 v74, 0x80, v82
	v_mov_b32_e32 v75, v83
	v_pk_add_f32 v[72:73], v[72:73], v[132:133]
	v_pk_add_f32 v[70:71], v[70:71], v[130:131]
	v_lshl_add_u64 v[76:77], v[74:75], 2, s[30:31]
	global_store_dwordx4 v[76:77], v[70:73], off nt
	v_mul_f32_e32 v76, v71, v71
	v_mul_f32_e32 v77, v73, v73
	v_add_f32_e32 v84, v84, v85
	v_add_f32_e32 v80, v80, v81
	v_fmac_f32_e32 v76, v70, v70
	v_fmac_f32_e32 v77, v72, v72
	v_add_f32_e32 v80, v84, v80
	v_add_f32_e32 v76, v76, v77
	v_add_f32_e32 v78, v80, v76
	v_cvt_pk_bf16_f32 v76, v70, v71
	v_pk_add_f32 v[70:71], v[68:69], v[128:129]
	v_pk_add_f32 v[68:69], v[66:67], v[126:127]
	v_mul_f32_e32 v67, v71, v71
	v_mul_f32_e32 v66, v69, v69
	v_fmac_f32_e32 v66, v68, v68
	v_fmac_f32_e32 v67, v70, v70
	v_add_f32_e32 v66, v66, v67
	v_cvt_pk_bf16_f32 v77, v72, v73
	v_lshl_add_u64 v[72:73], v[74:75], 1, s[36:37]
	v_add_f32_e32 v74, v78, v66
	ds_bpermute_b32 v75, v142, v74
	v_or_b32_e32 v82, 0x90, v82
	v_lshl_add_u64 v[66:67], v[82:83], 2, s[30:31]
	global_store_dwordx2 v[72:73], v[76:77], off
	global_store_dwordx4 v[66:67], v[68:71], off nt
	s_waitcnt lgkmcnt(0)
	v_add_f32_e32 v66, v74, v75
	ds_bpermute_b32 v67, v143, v66
	v_cvt_pk_bf16_f32 v68, v68, v69
	v_cvt_pk_bf16_f32 v69, v70, v71
	v_lshl_add_u64 v[70:71], v[82:83], 1, s[36:37]
	global_store_dwordx2 v[70:71], v[68:69], off
	s_and_saveexec_b64 s[4:5], s[40:41]
	s_cbranch_execz .LBB0_1238
	v_lshlrev_b64 v[68:69], 7, v[202:203]
	v_lshl_add_u64 v[68:69], s[44:45], 0, v[68:69]
	v_lshl_add_u64 v[68:69], s[56:57], 2, v[68:69]
	s_lshl_b32 s10, s23, 2
	v_lshl_add_u64 v[68:69], v[68:69], 0, s[10:11]
	s_waitcnt lgkmcnt(0)
	v_add_f32_e32 v66, v66, v67
	global_store_dword v[68:69], v66, off
.LBB0_1238:
	s_or_b64 exec, exec, s[4:5]
	v_add_u32_e32 v128, 0x80, v200
	v_ashrrev_i32_e32 v129, 31, v128
	s_waitcnt lgkmcnt(0)
	v_lshlrev_b64 v[66:67], 13, v[128:129]
	v_lshl_add_u64 v[66:67], v[198:199], 0, v[66:67]
	global_load_dwordx4 v[132:135], v[66:67], off nt
	global_load_dwordx4 v[136:139], v[66:67], off offset:64 nt
	global_load_dwordx4 v[118:121], v[66:67], off offset:512 nt
	global_load_dwordx4 v[114:117], v[66:67], off offset:576 nt
	v_add_u32_e32 v126, 0x90, v200
	v_ashrrev_i32_e32 v127, 31, v126
	v_lshlrev_b64 v[66:67], 13, v[126:127]
	v_add_u32_e32 v124, 0xa0, v200
	v_lshl_add_u64 v[66:67], v[198:199], 0, v[66:67]
	v_ashrrev_i32_e32 v125, 31, v124
	global_load_dwordx4 v[110:113], v[66:67], off nt
	global_load_dwordx4 v[106:109], v[66:67], off offset:64 nt
	global_load_dwordx4 v[102:105], v[66:67], off offset:512 nt
	global_load_dwordx4 v[98:101], v[66:67], off offset:576 nt
	v_lshlrev_b64 v[66:67], 13, v[124:125]
	v_add_u32_e32 v122, 0xb0, v200
	v_lshl_add_u64 v[66:67], v[198:199], 0, v[66:67]
	v_ashrrev_i32_e32 v123, 31, v122
	global_load_dwordx4 v[94:97], v[66:67], off nt
	global_load_dwordx4 v[90:93], v[66:67], off offset:64 nt
	global_load_dwordx4 v[82:85], v[66:67], off offset:512 nt
	global_load_dwordx4 v[74:77], v[66:67], off offset:576 nt
	v_lshlrev_b64 v[66:67], 13, v[122:123]
	v_lshl_add_u64 v[66:67], v[198:199], 0, v[66:67]
	global_load_dwordx4 v[86:89], v[66:67], off nt
	global_load_dwordx4 v[78:81], v[66:67], off offset:64 nt
	global_load_dwordx4 v[70:73], v[66:67], off offset:512 nt
	s_nop 0
	global_load_dwordx4 v[66:69], v[66:67], off offset:576 nt
	v_lshlrev_b64 v[130:131], 11, v[128:129]
	v_lshl_add_u64 v[130:131], v[130:131], 0, v[196:197]
	s_waitcnt vmcnt(15)
	v_pk_add_f32 v[64:65], v[64:65], v[134:135]
	v_pk_add_f32 v[62:63], v[62:63], v[132:133]
	v_lshl_add_u64 v[132:133], v[130:131], 2, s[30:31]
	global_store_dwordx4 v[132:133], v[62:65], off nt
	v_mul_f32_e32 v132, v63, v63
	v_mul_f32_e32 v133, v65, v65
	v_fmac_f32_e32 v132, v62, v62
	v_fmac_f32_e32 v133, v64, v64
	v_cvt_pk_bf16_f32 v62, v62, v63
	v_cvt_pk_bf16_f32 v63, v64, v65
	v_lshl_add_u64 v[64:65], v[130:131], 1, s[36:37]
	global_store_dwordx2 v[64:65], v[62:63], off
	v_or_b32_e32 v62, 16, v130
	v_mov_b32_e32 v63, v131
	s_waitcnt vmcnt(16)
	v_pk_add_f32 v[60:61], v[60:61], v[138:139]
	v_pk_add_f32 v[58:59], v[58:59], v[136:137]
	v_lshl_add_u64 v[64:65], v[62:63], 2, s[30:31]
	global_store_dwordx4 v[64:65], v[58:61], off nt
	v_mul_f32_e32 v64, v59, v59
	v_mul_f32_e32 v65, v61, v61
	v_fmac_f32_e32 v64, v58, v58
	v_fmac_f32_e32 v65, v60, v60
	v_cvt_pk_bf16_f32 v58, v58, v59
	v_cvt_pk_bf16_f32 v59, v60, v61
	v_lshl_add_u64 v[60:61], v[62:63], 1, s[36:37]
	global_store_dwordx2 v[60:61], v[58:59], off
	v_or_b32_e32 v58, 0x80, v130
	v_mov_b32_e32 v59, v131
	s_waitcnt vmcnt(17)
	v_pk_add_f32 v[56:57], v[56:57], v[120:121]
	v_pk_add_f32 v[54:55], v[54:55], v[118:119]
	v_lshl_add_u64 v[60:61], v[58:59], 2, s[30:31]
	global_store_dwordx4 v[60:61], v[54:57], off nt
	v_mul_f32_e32 v60, v55, v55
	v_mul_f32_e32 v61, v57, v57
	v_fmac_f32_e32 v60, v54, v54
	v_fmac_f32_e32 v61, v56, v56
	v_cvt_pk_bf16_f32 v54, v54, v55
	v_cvt_pk_bf16_f32 v55, v56, v57
	v_lshl_add_u64 v[56:57], v[58:59], 1, s[36:37]
	v_or_b32_e32 v130, 0x90, v130
	global_store_dwordx2 v[56:57], v[54:55], off
	s_waitcnt vmcnt(18)
	v_pk_add_f32 v[52:53], v[52:53], v[116:117]
	v_pk_add_f32 v[50:51], v[50:51], v[114:115]
	v_lshl_add_u64 v[54:55], v[130:131], 2, s[30:31]
	v_add_f32_e32 v132, v132, v133
	v_add_f32_e32 v64, v64, v65
	global_store_dwordx4 v[54:55], v[50:53], off nt
	v_mul_f32_e32 v54, v51, v51
	v_mul_f32_e32 v55, v53, v53
	v_add_f32_e32 v64, v132, v64
	v_add_f32_e32 v60, v60, v61
	v_fmac_f32_e32 v54, v50, v50
	v_fmac_f32_e32 v55, v52, v52
	v_add_f32_e32 v60, v64, v60
	v_add_f32_e32 v54, v54, v55
	v_add_f32_e32 v54, v60, v54
	v_cvt_pk_bf16_f32 v50, v50, v51
	v_cvt_pk_bf16_f32 v51, v52, v53
	v_lshl_add_u64 v[52:53], v[130:131], 1, s[36:37]
	global_store_dwordx2 v[52:53], v[50:51], off
	ds_bpermute_b32 v50, v142, v54
	s_waitcnt lgkmcnt(0)
	v_add_f32_e32 v50, v54, v50
	ds_bpermute_b32 v51, v143, v50
	s_and_saveexec_b64 s[4:5], s[40:41]
	s_cbranch_execz .LBB0_1240
	v_lshlrev_b64 v[52:53], 7, v[128:129]
	v_lshl_add_u64 v[52:53], s[44:45], 0, v[52:53]
	v_lshl_add_u64 v[52:53], s[56:57], 2, v[52:53]
	s_lshl_b32 s10, s23, 2
	v_lshl_add_u64 v[52:53], v[52:53], 0, s[10:11]
	s_waitcnt lgkmcnt(0)
	v_add_f32_e32 v50, v50, v51
	global_store_dword v[52:53], v50, off
.LBB0_1240:
	s_or_b64 exec, exec, s[4:5]
	s_waitcnt lgkmcnt(0)
	v_lshlrev_b64 v[50:51], 11, v[126:127]
	v_lshl_add_u64 v[50:51], v[50:51], 0, v[196:197]
	s_waitcnt vmcnt(19)
	v_pk_add_f32 v[48:49], v[48:49], v[112:113]
	v_pk_add_f32 v[46:47], v[46:47], v[110:111]
	v_lshl_add_u64 v[52:53], v[50:51], 2, s[30:31]
	global_store_dwordx4 v[52:53], v[46:49], off nt
	v_mul_f32_e32 v52, v47, v47
	v_mul_f32_e32 v53, v49, v49
	v_fmac_f32_e32 v52, v46, v46
	v_fmac_f32_e32 v53, v48, v48
	v_cvt_pk_bf16_f32 v46, v46, v47
	v_cvt_pk_bf16_f32 v47, v48, v49
	v_lshl_add_u64 v[48:49], v[50:51], 1, s[36:37]
	global_store_dwordx2 v[48:49], v[46:47], off
	v_or_b32_e32 v46, 16, v50
	v_mov_b32_e32 v47, v51
	s_waitcnt vmcnt(20)
	v_pk_add_f32 v[44:45], v[44:45], v[108:109]
	v_pk_add_f32 v[42:43], v[42:43], v[106:107]
	v_lshl_add_u64 v[48:49], v[46:47], 2, s[30:31]
	global_store_dwordx4 v[48:49], v[42:45], off nt
	v_mul_f32_e32 v48, v43, v43
	v_mul_f32_e32 v49, v45, v45
	v_fmac_f32_e32 v48, v42, v42
	v_fmac_f32_e32 v49, v44, v44
	v_cvt_pk_bf16_f32 v42, v42, v43
	v_cvt_pk_bf16_f32 v43, v44, v45
	v_lshl_add_u64 v[44:45], v[46:47], 1, s[36:37]
	global_store_dwordx2 v[44:45], v[42:43], off
	v_or_b32_e32 v42, 0x80, v50
	v_mov_b32_e32 v43, v51
	s_waitcnt vmcnt(21)
	v_pk_add_f32 v[40:41], v[40:41], v[104:105]
	v_pk_add_f32 v[38:39], v[38:39], v[102:103]
	v_lshl_add_u64 v[44:45], v[42:43], 2, s[30:31]
	global_store_dwordx4 v[44:45], v[38:41], off nt
	v_mul_f32_e32 v44, v39, v39
	v_mul_f32_e32 v45, v41, v41
	v_add_f32_e32 v52, v52, v53
	v_add_f32_e32 v48, v48, v49
	v_fmac_f32_e32 v44, v38, v38
	v_fmac_f32_e32 v45, v40, v40
	v_add_f32_e32 v48, v52, v48
	v_add_f32_e32 v44, v44, v45
	v_add_f32_e32 v46, v48, v44
	v_cvt_pk_bf16_f32 v44, v38, v39
	s_waitcnt vmcnt(21)
	v_pk_add_f32 v[38:39], v[36:37], v[100:101]
	v_pk_add_f32 v[36:37], v[34:35], v[98:99]
	v_mul_f32_e32 v35, v39, v39
	v_mul_f32_e32 v34, v37, v37
	v_fmac_f32_e32 v34, v36, v36
	v_fmac_f32_e32 v35, v38, v38
	v_add_f32_e32 v34, v34, v35
	v_cvt_pk_bf16_f32 v45, v40, v41
	v_lshl_add_u64 v[40:41], v[42:43], 1, s[36:37]
	v_add_f32_e32 v42, v46, v34
	ds_bpermute_b32 v43, v142, v42
	v_or_b32_e32 v50, 0x90, v50
	v_lshl_add_u64 v[34:35], v[50:51], 2, s[30:31]
	global_store_dwordx2 v[40:41], v[44:45], off
	global_store_dwordx4 v[34:35], v[36:39], off nt
	s_waitcnt lgkmcnt(0)
	v_add_f32_e32 v34, v42, v43
	ds_bpermute_b32 v35, v143, v34
	v_cvt_pk_bf16_f32 v36, v36, v37
	v_cvt_pk_bf16_f32 v37, v38, v39
	v_lshl_add_u64 v[38:39], v[50:51], 1, s[36:37]
	global_store_dwordx2 v[38:39], v[36:37], off
	s_and_saveexec_b64 s[4:5], s[40:41]
	s_cbranch_execz .LBB0_1242
	v_lshlrev_b64 v[36:37], 7, v[126:127]
	v_lshl_add_u64 v[36:37], s[44:45], 0, v[36:37]
	v_lshl_add_u64 v[36:37], s[56:57], 2, v[36:37]
	s_lshl_b32 s10, s23, 2
	v_lshl_add_u64 v[36:37], v[36:37], 0, s[10:11]
	s_waitcnt lgkmcnt(0)
	v_add_f32_e32 v34, v34, v35
	global_store_dword v[36:37], v34, off
.LBB0_1242:
	s_or_b64 exec, exec, s[4:5]
	s_waitcnt lgkmcnt(0)
	v_lshlrev_b64 v[34:35], 11, v[124:125]
	v_lshl_add_u64 v[34:35], v[34:35], 0, v[196:197]
	s_waitcnt vmcnt(23)
	v_pk_add_f32 v[32:33], v[32:33], v[96:97]
	v_pk_add_f32 v[30:31], v[30:31], v[94:95]
	v_lshl_add_u64 v[36:37], v[34:35], 2, s[30:31]
	global_store_dwordx4 v[36:37], v[30:33], off nt
	v_mul_f32_e32 v36, v31, v31
	v_mul_f32_e32 v37, v33, v33
	v_fmac_f32_e32 v36, v30, v30
	v_fmac_f32_e32 v37, v32, v32
	v_cvt_pk_bf16_f32 v30, v30, v31
	v_cvt_pk_bf16_f32 v31, v32, v33
	v_lshl_add_u64 v[32:33], v[34:35], 1, s[36:37]
	global_store_dwordx2 v[32:33], v[30:31], off
	v_or_b32_e32 v30, 16, v34
	v_mov_b32_e32 v31, v35
	s_waitcnt vmcnt(24)
	v_pk_add_f32 v[28:29], v[28:29], v[92:93]
	v_pk_add_f32 v[26:27], v[26:27], v[90:91]
	v_lshl_add_u64 v[32:33], v[30:31], 2, s[30:31]
	global_store_dwordx4 v[32:33], v[26:29], off nt
	v_mul_f32_e32 v32, v27, v27
	v_mul_f32_e32 v33, v29, v29
	v_fmac_f32_e32 v32, v26, v26
	v_fmac_f32_e32 v33, v28, v28
	v_cvt_pk_bf16_f32 v26, v26, v27
	v_cvt_pk_bf16_f32 v27, v28, v29
	v_lshl_add_u64 v[28:29], v[30:31], 1, s[36:37]
	global_store_dwordx2 v[28:29], v[26:27], off
	v_or_b32_e32 v26, 0x80, v34
	v_mov_b32_e32 v27, v35
	s_waitcnt vmcnt(25)
	v_pk_add_f32 v[24:25], v[24:25], v[84:85]
	v_pk_add_f32 v[22:23], v[22:23], v[82:83]
	v_lshl_add_u64 v[28:29], v[26:27], 2, s[30:31]
	global_store_dwordx4 v[28:29], v[22:25], off nt
	v_mul_f32_e32 v28, v23, v23
	v_mul_f32_e32 v29, v25, v25
	v_add_f32_e32 v36, v36, v37
	v_add_f32_e32 v32, v32, v33
	v_fmac_f32_e32 v28, v22, v22
	v_fmac_f32_e32 v29, v24, v24
	v_add_f32_e32 v32, v36, v32
	v_add_f32_e32 v28, v28, v29
	v_add_f32_e32 v30, v32, v28
	v_cvt_pk_bf16_f32 v28, v22, v23
	s_waitcnt vmcnt(25)
	v_pk_add_f32 v[22:23], v[20:21], v[76:77]
	v_pk_add_f32 v[20:21], v[18:19], v[74:75]
	v_mul_f32_e32 v19, v23, v23
	v_mul_f32_e32 v18, v21, v21
	v_fmac_f32_e32 v18, v20, v20
	v_fmac_f32_e32 v19, v22, v22
	v_add_f32_e32 v18, v18, v19
	v_cvt_pk_bf16_f32 v29, v24, v25
	v_lshl_add_u64 v[24:25], v[26:27], 1, s[36:37]
	v_add_f32_e32 v26, v30, v18
	ds_bpermute_b32 v27, v142, v26
	v_or_b32_e32 v34, 0x90, v34
	v_lshl_add_u64 v[18:19], v[34:35], 2, s[30:31]
	global_store_dwordx2 v[24:25], v[28:29], off
	global_store_dwordx4 v[18:19], v[20:23], off nt
	s_waitcnt lgkmcnt(0)
	v_add_f32_e32 v18, v26, v27
	ds_bpermute_b32 v19, v143, v18
	v_cvt_pk_bf16_f32 v20, v20, v21
	v_cvt_pk_bf16_f32 v21, v22, v23
	v_lshl_add_u64 v[22:23], v[34:35], 1, s[36:37]
	global_store_dwordx2 v[22:23], v[20:21], off
	s_and_saveexec_b64 s[4:5], s[40:41]
	s_cbranch_execz .LBB0_1244
	v_lshlrev_b64 v[20:21], 7, v[124:125]
	v_lshl_add_u64 v[20:21], s[44:45], 0, v[20:21]
	v_lshl_add_u64 v[20:21], s[56:57], 2, v[20:21]
	s_lshl_b32 s10, s23, 2
	v_lshl_add_u64 v[20:21], v[20:21], 0, s[10:11]
	s_waitcnt lgkmcnt(0)
	v_add_f32_e32 v18, v18, v19
	global_store_dword v[20:21], v18, off
.LBB0_1244:
	s_or_b64 exec, exec, s[4:5]
	s_waitcnt lgkmcnt(0)
	v_lshlrev_b64 v[18:19], 11, v[122:123]
	v_lshl_add_u64 v[18:19], v[18:19], 0, v[196:197]
	s_waitcnt vmcnt(27)
	v_pk_add_f32 v[16:17], v[16:17], v[88:89]
	v_pk_add_f32 v[14:15], v[14:15], v[86:87]
	v_lshl_add_u64 v[20:21], v[18:19], 2, s[30:31]
	global_store_dwordx4 v[20:21], v[14:17], off nt
	v_mul_f32_e32 v20, v15, v15
	v_mul_f32_e32 v21, v17, v17
	v_fmac_f32_e32 v20, v14, v14
	v_fmac_f32_e32 v21, v16, v16
	v_cvt_pk_bf16_f32 v14, v14, v15
	v_cvt_pk_bf16_f32 v15, v16, v17
	v_lshl_add_u64 v[16:17], v[18:19], 1, s[36:37]
	global_store_dwordx2 v[16:17], v[14:15], off
	v_or_b32_e32 v14, 16, v18
	v_mov_b32_e32 v15, v19
	s_waitcnt vmcnt(28)
	v_pk_add_f32 v[12:13], v[12:13], v[80:81]
	v_pk_add_f32 v[10:11], v[10:11], v[78:79]
	v_lshl_add_u64 v[16:17], v[14:15], 2, s[30:31]
	global_store_dwordx4 v[16:17], v[10:13], off nt
	v_mul_f32_e32 v16, v11, v11
	v_mul_f32_e32 v17, v13, v13
	v_fmac_f32_e32 v16, v10, v10
	v_fmac_f32_e32 v17, v12, v12
	v_cvt_pk_bf16_f32 v10, v10, v11
	v_cvt_pk_bf16_f32 v11, v12, v13
	v_lshl_add_u64 v[12:13], v[14:15], 1, s[36:37]
	global_store_dwordx2 v[12:13], v[10:11], off
	v_or_b32_e32 v10, 0x80, v18
	v_mov_b32_e32 v11, v19
	s_waitcnt vmcnt(29)
	v_pk_add_f32 v[8:9], v[8:9], v[72:73]
	v_pk_add_f32 v[6:7], v[6:7], v[70:71]
	v_lshl_add_u64 v[12:13], v[10:11], 2, s[30:31]
	global_store_dwordx4 v[12:13], v[6:9], off nt
	v_mul_f32_e32 v12, v7, v7
	v_mul_f32_e32 v13, v9, v9
	v_add_f32_e32 v20, v20, v21
	v_add_f32_e32 v16, v16, v17
	v_fmac_f32_e32 v12, v6, v6
	v_fmac_f32_e32 v13, v8, v8
	v_add_f32_e32 v16, v20, v16
	v_add_f32_e32 v12, v12, v13
	v_add_f32_e32 v14, v16, v12
	v_cvt_pk_bf16_f32 v12, v6, v7
	s_waitcnt vmcnt(29)
	v_pk_add_f32 v[6:7], v[4:5], v[68:69]
	v_pk_add_f32 v[4:5], v[2:3], v[66:67]
	v_mul_f32_e32 v3, v7, v7
	v_mul_f32_e32 v2, v5, v5
	v_fmac_f32_e32 v2, v4, v4
	v_fmac_f32_e32 v3, v6, v6
	v_add_f32_e32 v2, v2, v3
	v_cvt_pk_bf16_f32 v13, v8, v9
	v_lshl_add_u64 v[8:9], v[10:11], 1, s[36:37]
	v_add_f32_e32 v10, v14, v2
	ds_bpermute_b32 v11, v142, v10
	v_or_b32_e32 v18, 0x90, v18
	v_lshl_add_u64 v[2:3], v[18:19], 2, s[30:31]
	global_store_dwordx2 v[8:9], v[12:13], off
	global_store_dwordx4 v[2:3], v[4:7], off nt
	s_waitcnt lgkmcnt(0)
	v_add_f32_e32 v2, v10, v11
	ds_bpermute_b32 v3, v143, v2
	v_cvt_pk_bf16_f32 v4, v4, v5
	v_cvt_pk_bf16_f32 v5, v6, v7
	v_lshl_add_u64 v[6:7], v[18:19], 1, s[36:37]
	global_store_dwordx2 v[6:7], v[4:5], off
	s_and_saveexec_b64 s[4:5], s[40:41]
	s_cbranch_execz .LBB0_1246
	v_lshlrev_b64 v[4:5], 7, v[122:123]
	v_lshl_add_u64 v[4:5], s[44:45], 0, v[4:5]
	v_lshl_add_u64 v[4:5], s[56:57], 2, v[4:5]
	s_lshl_b32 s10, s23, 2
	v_lshl_add_u64 v[4:5], v[4:5], 0, s[10:11]
	s_waitcnt lgkmcnt(0)
	v_add_f32_e32 v2, v2, v3
	global_store_dword v[4:5], v2, off

.LBB0_1425:
	v_lshl_add_u32 v200, s58, 8, v231
	v_lshl_or_b32 v196, s56, 8, v233
	v_ashrrev_i32_e32 v197, 31, v196
	v_ashrrev_i32_e32 v201, 31, v200
	v_lshl_add_u64 v[198:199], v[196:197], 2, s[18:19]
	v_lshlrev_b64 v[126:127], 13, v[200:201]
	v_lshl_add_u64 v[126:127], v[198:199], 0, v[126:127]
	global_load_dwordx4 v[186:189], v[126:127], off nt
	global_load_dwordx4 v[218:221], v[126:127], off offset:64 nt
	global_load_dwordx4 v[182:185], v[126:127], off offset:512 nt
	global_load_dwordx4 v[178:181], v[126:127], off offset:576 nt
	v_or_b32_e32 v206, 16, v200
	v_ashrrev_i32_e32 v207, 31, v206
	v_lshlrev_b64 v[126:127], 13, v[206:207]
	v_or_b32_e32 v204, 32, v200
	v_lshl_add_u64 v[126:127], v[198:199], 0, v[126:127]
	v_ashrrev_i32_e32 v205, 31, v204
	global_load_dwordx4 v[174:177], v[126:127], off nt
	global_load_dwordx4 v[170:173], v[126:127], off offset:64 nt
	global_load_dwordx4 v[166:169], v[126:127], off offset:512 nt
	global_load_dwordx4 v[162:165], v[126:127], off offset:576 nt
	v_lshlrev_b64 v[126:127], 13, v[204:205]
	v_or_b32_e32 v202, 48, v200
	v_lshl_add_u64 v[126:127], v[198:199], 0, v[126:127]
	v_ashrrev_i32_e32 v203, 31, v202
	global_load_dwordx4 v[158:161], v[126:127], off nt
	global_load_dwordx4 v[154:157], v[126:127], off offset:64 nt
	global_load_dwordx4 v[146:149], v[126:127], off offset:512 nt
	global_load_dwordx4 v[134:137], v[126:127], off offset:576 nt
	v_lshlrev_b64 v[126:127], 13, v[202:203]
	v_lshl_add_u64 v[126:127], v[198:199], 0, v[126:127]
	global_load_dwordx4 v[150:153], v[126:127], off nt
	global_load_dwordx4 v[138:141], v[126:127], off offset:64 nt
	global_load_dwordx4 v[130:133], v[126:127], off offset:512 nt
	s_nop 0
	global_load_dwordx4 v[126:129], v[126:127], off offset:576 nt
	v_lshlrev_b64 v[208:209], 11, v[200:201]
	v_lshl_add_u64 v[208:209], v[208:209], 0, v[196:197]
	s_lshl_b32 s56, s56, 2
	s_ashr_i32 s57, s56, 31
	s_waitcnt vmcnt(0)
	v_pk_add_f32 v[144:145], v[144:145], v[188:189]
	v_pk_add_f32 v[142:143], v[142:143], v[186:187]
	v_lshl_add_u64 v[186:187], v[208:209], 2, s[30:31]
	global_store_dwordx4 v[186:187], v[142:145], off nt
	v_mul_f32_e32 v186, v143, v143
	v_mul_f32_e32 v187, v145, v145
	v_fmac_f32_e32 v186, v142, v142
	v_fmac_f32_e32 v187, v144, v144
	v_cvt_pk_bf16_f32 v142, v142, v143
	v_cvt_pk_bf16_f32 v143, v144, v145
	v_lshl_add_u64 v[144:145], v[208:209], 1, s[36:37]
	global_store_dwordx2 v[144:145], v[142:143], off
	v_or_b32_e32 v142, 16, v208
	v_mov_b32_e32 v143, v209
	v_pk_add_f32 v[124:125], v[124:125], v[220:221]
	v_pk_add_f32 v[122:123], v[122:123], v[218:219]
	v_lshl_add_u64 v[144:145], v[142:143], 2, s[30:31]
	global_store_dwordx4 v[144:145], v[122:125], off nt
	v_mul_f32_e32 v144, v123, v123
	v_mul_f32_e32 v145, v125, v125
	v_fmac_f32_e32 v144, v122, v122
	v_fmac_f32_e32 v145, v124, v124
	v_cvt_pk_bf16_f32 v122, v122, v123
	v_cvt_pk_bf16_f32 v123, v124, v125
	v_lshl_add_u64 v[124:125], v[142:143], 1, s[36:37]
	global_store_dwordx2 v[124:125], v[122:123], off
	v_or_b32_e32 v122, 0x80, v208
	v_mov_b32_e32 v123, v209
	v_pk_add_f32 v[120:121], v[120:121], v[184:185]
	v_pk_add_f32 v[118:119], v[118:119], v[182:183]
	v_lshl_add_u64 v[124:125], v[122:123], 2, s[30:31]
	global_store_dwordx4 v[124:125], v[118:121], off nt
	v_mul_f32_e32 v124, v119, v119
	v_mul_f32_e32 v125, v121, v121
	v_fmac_f32_e32 v124, v118, v118
	v_fmac_f32_e32 v125, v120, v120
	v_cvt_pk_bf16_f32 v118, v118, v119
	v_cvt_pk_bf16_f32 v119, v120, v121
	v_lshl_add_u64 v[120:121], v[122:123], 1, s[36:37]
	v_or_b32_e32 v208, 0x90, v208
	global_store_dwordx2 v[120:121], v[118:119], off
	v_pk_add_f32 v[116:117], v[116:117], v[180:181]
	v_pk_add_f32 v[114:115], v[114:115], v[178:179]
	v_lshl_add_u64 v[118:119], v[208:209], 2, s[30:31]
	global_store_dwordx4 v[118:119], v[114:117], off nt
	v_mul_f32_e32 v118, v115, v115
	v_mul_f32_e32 v119, v117, v117
	v_fmac_f32_e32 v118, v114, v114
	v_fmac_f32_e32 v119, v116, v116
	v_cvt_pk_bf16_f32 v114, v114, v115
	v_cvt_pk_bf16_f32 v115, v116, v117
	v_lshl_add_u64 v[116:117], v[208:209], 1, s[36:37]
	v_add_f32_e32 v186, v186, v187
	v_add_f32_e32 v144, v144, v145
	global_store_dwordx2 v[116:117], v[114:115], off
	v_xor_b32_e32 v114, 16, v213
	v_add_f32_e32 v144, v186, v144
	v_add_f32_e32 v124, v124, v125
	v_cmp_lt_i32_e32 vcc, v114, v216
	v_add_f32_e32 v124, v144, v124
	v_add_f32_e32 v118, v118, v119
	v_cndmask_b32_e32 v114, v213, v114, vcc
	v_add_f32_e32 v118, v124, v118
	v_lshlrev_b32_e32 v142, 2, v114
	ds_bpermute_b32 v114, v142, v118
	v_xor_b32_e32 v115, 32, v213
	v_cmp_lt_i32_e32 vcc, v115, v216
	s_waitcnt lgkmcnt(0)
	v_add_f32_e32 v114, v118, v114
	v_cndmask_b32_e32 v115, v213, v115, vcc
	v_lshlrev_b32_e32 v143, 2, v115
	ds_bpermute_b32 v115, v143, v114
	s_and_saveexec_b64 s[4:5], s[40:41]
	s_cbranch_execz .LBB0_1427
	v_lshlrev_b64 v[116:117], 7, v[200:201]
	v_lshl_add_u64 v[116:117], s[44:45], 0, v[116:117]
	v_lshl_add_u64 v[116:117], s[56:57], 2, v[116:117]
	s_lshl_b32 s10, s23, 2
	v_lshl_add_u64 v[116:117], v[116:117], 0, s[10:11]
	s_waitcnt lgkmcnt(0)
	v_add_f32_e32 v114, v114, v115
	global_store_dword v[116:117], v114, off
